# 64-byte alignment of the hot inner loop heads (GEMM K-loops, attention main loop, LN loop)
# baseline (speedup 1.0000x reference)
; template <class Epi, class Sched>
; __device__ __forceinline__ void gemm_phase(PG8_LAS unsigned char* lds, const Gemm g, const Sched& S, const Epi& E) {
;     ...
;         const bool has_next = S.next(ui + 1, nxt);
;         const char* nA = has_next ? (const char*)g.A + (size_t)nxt.pm * tstep : cA; const char* nB = has_next ? (const char*)g.Bt + (size_t)nxt.pn * tstep : cB;
;         for (int t = 0; t < nt; t += 2) {
;             const bool last = (t == nt - 2);
;             const char* a1 = cA + (size_t)(t + 1) * kstep;
;             const char* a2 = last ? nA : cA + (size_t)(t + 2) * kstep; const char* b2 = last ? nB : cB + (size_t)(t + 2) * kstep;
;             const char* a3 = a2 + kstep; const char* b3 = b2 + kstep;
;     ...
; #pragma unroll
;         for (int a = 0; a < 2; ++a)
; #pragma unroll
;             for (int b = 0; b < 2; ++b)
; #pragma unroll
;                 for (int m = 0; m < 4; ++m)
; #pragma unroll
;                     for (int n = 0; n < 2; ++n) acc[a][b][m][n] = (f32x4){0.f, 0.f, 0.f, 0.f};
;         cur = nxt; cA = nA; cB = nB; ++ui;
.LBB0_184:
	v_mov_b64_e32 v[0:1], 0x880
	s_ashr_i32 s7, s6, 31
	v_cmp_lt_i64_e32 vcc, s[8:9], v[0:1]
	s_lshl_b64 s[8:9], s[6:7], 19
	s_add_u32 s8, s90, s8
	s_addc_u32 s9, s91, s9
	s_and_b64 s[10:11], vcc, exec
	s_cselect_b32 s7, s9, s15
	s_cselect_b32 s13, s8, s14
	s_ashr_i32 s1, s0, 31
	s_lshl_b64 s[10:11], s[0:1], 19
	s_add_u32 s10, s28, s10
	s_addc_u32 s11, s29, s11
	s_and_b64 s[18:19], vcc, exec
	s_cselect_b32 s1, s11, s17
	s_cselect_b32 s76, s10, s16
	s_add_u32 s14, s14, 0x40080
	s_addc_u32 s15, s15, 0
	s_add_u32 s77, s16, 0x100
	v_mov_b32_e32 v0, 0
	s_addc_u32 s78, s17, 0
	s_mov_b32 s79, -2
	v_mov_b32_e32 v1, v0
	v_mov_b32_e32 v2, v0
	v_mov_b32_e32 v3, v0
	v_mov_b32_e32 v8, v0
	v_mov_b32_e32 v9, v0
	v_mov_b32_e32 v10, v0
	v_mov_b32_e32 v11, v0
	v_mov_b32_e32 v16, v0
	v_mov_b32_e32 v17, v0
	v_mov_b32_e32 v18, v0
	v_mov_b32_e32 v19, v0
	v_mov_b32_e32 v24, v0
	v_mov_b32_e32 v25, v0
	v_mov_b32_e32 v26, v0
	v_mov_b32_e32 v27, v0
	v_mov_b32_e32 v32, v0
	v_mov_b32_e32 v33, v0
	v_mov_b32_e32 v34, v0
	v_mov_b32_e32 v35, v0
	v_mov_b32_e32 v40, v0
	v_mov_b32_e32 v41, v0
	v_mov_b32_e32 v42, v0
	v_mov_b32_e32 v43, v0
	v_mov_b32_e32 v48, v0
	v_mov_b32_e32 v49, v0
	v_mov_b32_e32 v50, v0
	v_mov_b32_e32 v51, v0
	v_mov_b32_e32 v56, v0
	v_mov_b32_e32 v57, v0
	v_mov_b32_e32 v58, v0
	v_mov_b32_e32 v59, v0
	v_mov_b32_e32 v4, v0
	v_mov_b32_e32 v5, v0
	v_mov_b32_e32 v6, v0
	v_mov_b32_e32 v7, v0
	v_mov_b32_e32 v12, v0
	v_mov_b32_e32 v13, v0
	v_mov_b32_e32 v14, v0
	v_mov_b32_e32 v15, v0
	v_mov_b32_e32 v20, v0
	v_mov_b32_e32 v21, v0
	v_mov_b32_e32 v22, v0
	v_mov_b32_e32 v23, v0
	v_mov_b32_e32 v28, v0
	v_mov_b32_e32 v29, v0
	v_mov_b32_e32 v30, v0
	v_mov_b32_e32 v31, v0
	v_mov_b32_e32 v36, v0
	v_mov_b32_e32 v37, v0
	v_mov_b32_e32 v38, v0
	v_mov_b32_e32 v39, v0
	v_mov_b32_e32 v44, v0
	v_mov_b32_e32 v45, v0
	v_mov_b32_e32 v46, v0
	v_mov_b32_e32 v47, v0
	v_mov_b32_e32 v52, v0
	v_mov_b32_e32 v53, v0
	v_mov_b32_e32 v54, v0
	v_mov_b32_e32 v55, v0
	v_mov_b32_e32 v60, v0
	v_mov_b32_e32 v61, v0
	v_mov_b32_e32 v62, v0
	v_mov_b32_e32 v63, v0
	v_mov_b32_e32 v64, v0
	v_mov_b32_e32 v65, v0
	v_mov_b32_e32 v66, v0
	v_mov_b32_e32 v67, v0
	v_mov_b32_e32 v72, v0
	v_mov_b32_e32 v73, v0
	v_mov_b32_e32 v74, v0
	v_mov_b32_e32 v75, v0
	v_mov_b32_e32 v80, v0
	v_mov_b32_e32 v81, v0
	v_mov_b32_e32 v82, v0
	v_mov_b32_e32 v83, v0
	v_mov_b32_e32 v88, v0
	v_mov_b32_e32 v89, v0
	v_mov_b32_e32 v90, v0
	v_mov_b32_e32 v91, v0
	v_mov_b32_e32 v96, v0
	v_mov_b32_e32 v97, v0
	v_mov_b32_e32 v98, v0
	v_mov_b32_e32 v99, v0
	v_mov_b32_e32 v104, v0
	v_mov_b32_e32 v105, v0
	v_mov_b32_e32 v106, v0
	v_mov_b32_e32 v107, v0
	v_mov_b32_e32 v112, v0
	v_mov_b32_e32 v113, v0
	v_mov_b32_e32 v114, v0
	v_mov_b32_e32 v115, v0
	v_mov_b32_e32 v120, v0
	v_mov_b32_e32 v121, v0
	v_mov_b32_e32 v122, v0
	v_mov_b32_e32 v123, v0
	v_mov_b32_e32 v68, v0
	v_mov_b32_e32 v69, v0
	v_mov_b32_e32 v70, v0
	v_mov_b32_e32 v71, v0
	v_mov_b32_e32 v76, v0
	v_mov_b32_e32 v77, v0
	v_mov_b32_e32 v78, v0
	v_mov_b32_e32 v79, v0
	v_mov_b32_e32 v84, v0
	v_mov_b32_e32 v85, v0
	v_mov_b32_e32 v86, v0
	v_mov_b32_e32 v87, v0
	v_mov_b32_e32 v92, v0
	v_mov_b32_e32 v93, v0
	v_mov_b32_e32 v94, v0
	v_mov_b32_e32 v95, v0
	v_mov_b32_e32 v100, v0
	v_mov_b32_e32 v101, v0
	v_mov_b32_e32 v102, v0
	v_mov_b32_e32 v103, v0
	v_mov_b32_e32 v108, v0
	v_mov_b32_e32 v109, v0
	v_mov_b32_e32 v110, v0
	v_mov_b32_e32 v111, v0
	v_mov_b32_e32 v116, v0
	v_mov_b32_e32 v117, v0
	v_mov_b32_e32 v118, v0
	v_mov_b32_e32 v119, v0
	v_mov_b32_e32 v124, v0
	v_mov_b32_e32 v125, v0
	v_mov_b32_e32 v126, v0
	v_mov_b32_e32 v127, v0
	.p2align	6

; DI unsigned xb_ld(unsigned* p)              { return __hip_atomic_load(p, __ATOMIC_RELAXED, __HIP_MEMORY_SCOPE_AGENT); }
; DI void xcd_barrier_complete(unsigned* bar, unsigned x, unsigned& nloc, unsigned& nx) {
;     ...
;     for (;;) {
;         sum = 0u; cnt = 0u; mine = 0u;
; #pragma unroll
;         for (unsigned j = 0; j < 16; ++j) { const unsigned c = xb_ld(&bar[XB_XCNT(j)]); sum += c; cnt += (c > 0u) ? 1u : 0u; mine = (j == x) ? c : mine; }
;         if (sum == G) break;
;         __builtin_amdgcn_s_sleep(1);
;         if ((++sp & 255u) == 0u) { if (xb_ld(&bar[XB_TMO])) break; if (sp > XB_SPIN_CAP) { atomicAdd(&bar[XB_TMO], 1u); break; } }
;     }
.LBB0_308:
	s_and_b64 vcc, exec, s[74:75]
	s_cbranch_vccnz .LBB0_316
	.p2align	6

; DI unsigned xb_ld(unsigned* p)              { return __hip_atomic_load(p, __ATOMIC_RELAXED, __HIP_MEMORY_SCOPE_AGENT); }
; #define XB_SPIN(cond, bar) do { unsigned _sp = 0; while (cond) { __builtin_amdgcn_s_sleep(1); \
;     if ((++_sp & 255u) == 0u) { if (xb_ld(&(bar)[XB_TMO])) break; if (_sp > XB_SPIN_CAP) { atomicAdd(&(bar)[XB_TMO], 1u); break; } } } } while (0)
; DI void xcd_barrier(const XcdBarrier& b) {
;     ...
;             else XB_SPIN(xb_ld(&bar[XB_TOPGEN]) == tg, bar);
.LBB0_326:
	s_and_b64 s[70:71], exec, s[70:71]
	s_or_b64 s[80:81], s[70:71], s[80:81]
	s_andn2_b64 s[70:71], s[82:83], exec
	s_and_b64 s[46:47], s[46:47], exec
	s_or_b64 s[82:83], s[70:71], s[46:47]
	s_andn2_b64 exec, exec, s[80:81]
	s_cbranch_execz .LBB0_333
	.p2align	6

; DI unsigned xb_ld(unsigned* p)              { return __hip_atomic_load(p, __ATOMIC_RELAXED, __HIP_MEMORY_SCOPE_AGENT); }
; #define XB_SPIN(cond, bar) do { unsigned _sp = 0; while (cond) { __builtin_amdgcn_s_sleep(1); \
;     if ((++_sp & 255u) == 0u) { if (xb_ld(&(bar)[XB_TMO])) break; if (_sp > XB_SPIN_CAP) { atomicAdd(&(bar)[XB_TMO], 1u); break; } } } } while (0)
; DI void xcd_barrier(const XcdBarrier& b) {
;     ...
;             XB_SPIN(xb_ld(&bar[XB_XGEN(b.x)]) == gen, bar);
.LBB0_343:
	s_xor_b64 s[46:47], s[46:47], -1
	s_and_b64 s[70:71], exec, s[82:83]
	s_or_b64 s[78:79], s[70:71], s[78:79]
	s_andn2_b64 s[70:71], s[80:81], exec
	s_and_b64 s[46:47], s[46:47], exec
	s_or_b64 s[80:81], s[70:71], s[46:47]
	s_andn2_b64 exec, exec, s[78:79]
	s_cbranch_execz .LBB0_350
	.p2align	6

; DI unsigned xb_ld(unsigned* p)              { return __hip_atomic_load(p, __ATOMIC_RELAXED, __HIP_MEMORY_SCOPE_AGENT); }
; DI void xcd_barrier_complete(unsigned* bar, unsigned x, unsigned& nloc, unsigned& nx) {
;     ...
;     for (;;) {
;         sum = 0u; cnt = 0u; mine = 0u;
; #pragma unroll
;         for (unsigned j = 0; j < 16; ++j) { const unsigned c = xb_ld(&bar[XB_XCNT(j)]); sum += c; cnt += (c > 0u) ? 1u : 0u; mine = (j == x) ? c : mine; }
;         if (sum == G) break;
;         __builtin_amdgcn_s_sleep(1);
;         if ((++sp & 255u) == 0u) { if (xb_ld(&bar[XB_TMO])) break; if (sp > XB_SPIN_CAP) { atomicAdd(&bar[XB_TMO], 1u); break; } }
;     }
.LBB0_389:
	s_and_b64 vcc, exec, s[72:73]
	s_cbranch_vccnz .LBB0_397
	.p2align	6

; DI unsigned xb_ld(unsigned* p)              { return __hip_atomic_load(p, __ATOMIC_RELAXED, __HIP_MEMORY_SCOPE_AGENT); }
; #define XB_SPIN(cond, bar) do { unsigned _sp = 0; while (cond) { __builtin_amdgcn_s_sleep(1); \
;     if ((++_sp & 255u) == 0u) { if (xb_ld(&(bar)[XB_TMO])) break; if (_sp > XB_SPIN_CAP) { atomicAdd(&(bar)[XB_TMO], 1u); break; } } } } while (0)
; DI void xcd_barrier(const XcdBarrier& b) {
;     ...
;             else XB_SPIN(xb_ld(&bar[XB_TOPGEN]) == tg, bar);
.LBB0_407:
	s_and_b64 s[82:83], exec, s[82:83]
	s_or_b64 s[78:79], s[82:83], s[78:79]
	s_andn2_b64 s[80:81], s[80:81], exec
	s_and_b64 s[46:47], s[46:47], exec
	s_or_b64 s[80:81], s[80:81], s[46:47]
	s_andn2_b64 exec, exec, s[78:79]
	s_cbranch_execz .LBB0_414
	.p2align	6

; DI unsigned xb_ld(unsigned* p)              { return __hip_atomic_load(p, __ATOMIC_RELAXED, __HIP_MEMORY_SCOPE_AGENT); }
; #define XB_SPIN(cond, bar) do { unsigned _sp = 0; while (cond) { __builtin_amdgcn_s_sleep(1); \
;     if ((++_sp & 255u) == 0u) { if (xb_ld(&(bar)[XB_TMO])) break; if (_sp > XB_SPIN_CAP) { atomicAdd(&(bar)[XB_TMO], 1u); break; } } } } while (0)
; DI void xcd_barrier(const XcdBarrier& b) {
;     ...
;             XB_SPIN(xb_ld(&bar[XB_XGEN(b.x)]) == gen, bar);
.LBB0_424:
	s_xor_b64 s[46:47], s[46:47], -1
	s_and_b64 s[80:81], exec, s[80:81]
	s_or_b64 s[76:77], s[80:81], s[76:77]
	s_andn2_b64 s[78:79], s[78:79], exec
	s_and_b64 s[46:47], s[46:47], exec
	s_or_b64 s[78:79], s[78:79], s[46:47]
	s_andn2_b64 exec, exec, s[76:77]
	s_cbranch_execz .LBB0_431
	.p2align	6

; template <class Epi, class Sched>
; __device__ __forceinline__ void gemm_phase(PG8_LAS unsigned char* lds, const Gemm g, const Sched& S, const Epi& E) {
;     ...
;         const bool has_next = S.next(ui + 1, nxt);
;         const char* nA = has_next ? (const char*)g.A + (size_t)nxt.pm * tstep : cA; const char* nB = has_next ? (const char*)g.Bt + (size_t)nxt.pn * tstep : cB;
;         for (int t = 0; t < nt; t += 2) {
;             const bool last = (t == nt - 2);
;             const char* a1 = cA + (size_t)(t + 1) * kstep;
;             const char* a2 = last ? nA : cA + (size_t)(t + 2) * kstep; const char* b2 = last ? nB : cB + (size_t)(t + 2) * kstep;
;             const char* a3 = a2 + kstep; const char* b3 = b2 + kstep;
;     ...
; #pragma unroll
;         for (int a = 0; a < 2; ++a)
; #pragma unroll
;             for (int b = 0; b < 2; ++b)
; #pragma unroll
;                 for (int m = 0; m < 4; ++m)
; #pragma unroll
;                     for (int n = 0; n < 2; ++n) acc[a][b][m][n] = (f32x4){0.f, 0.f, 0.f, 0.f};
;         cur = nxt; cA = nA; cB = nB; ++ui;
.LBB0_515:
	v_mov_b64_e32 v[0:1], s[0:1]
	s_ashr_i32 s11, s10, 31
	v_cmp_lt_i64_e32 vcc, s[12:13], v[0:1]
	s_lshl_b64 s[12:13], s[10:11], 19
	s_add_u32 s12, s90, s12
	s_addc_u32 s13, s91, s13
	s_and_b64 s[14:15], vcc, exec
	s_cselect_b32 s11, s13, s21
	s_cselect_b32 s17, s12, s20
	s_ashr_i32 s9, s8, 31
	s_lshl_b64 s[14:15], s[8:9], 19
	s_add_u32 s14, s52, s14
	s_addc_u32 s15, s53, s15
	s_and_b64 s[72:73], vcc, exec
	s_cselect_b32 s9, s15, s71
	s_cselect_b32 s82, s14, s70
	s_add_u32 s20, s20, 0x40080
	s_addc_u32 s21, s21, 0
	s_add_u32 s83, s70, 0x100
	v_mov_b32_e32 v0, 0
	s_addc_u32 s88, s71, 0
	s_mov_b32 s89, -2
	v_mov_b32_e32 v1, v0
	v_mov_b32_e32 v2, v0
	v_mov_b32_e32 v3, v0
	v_mov_b32_e32 v4, v0
	v_mov_b32_e32 v5, v0
	v_mov_b32_e32 v6, v0
	v_mov_b32_e32 v7, v0
	v_mov_b32_e32 v16, v0
	v_mov_b32_e32 v17, v0
	v_mov_b32_e32 v18, v0
	v_mov_b32_e32 v19, v0
	v_mov_b32_e32 v20, v0
	v_mov_b32_e32 v21, v0
	v_mov_b32_e32 v22, v0
	v_mov_b32_e32 v23, v0
	v_mov_b32_e32 v32, v0
	v_mov_b32_e32 v33, v0
	v_mov_b32_e32 v34, v0
	v_mov_b32_e32 v35, v0
	v_mov_b32_e32 v36, v0
	v_mov_b32_e32 v37, v0
	v_mov_b32_e32 v38, v0
	v_mov_b32_e32 v39, v0
	v_mov_b32_e32 v52, v0
	v_mov_b32_e32 v53, v0
	v_mov_b32_e32 v54, v0
	v_mov_b32_e32 v55, v0
	v_mov_b32_e32 v64, v0
	v_mov_b32_e32 v65, v0
	v_mov_b32_e32 v66, v0
	v_mov_b32_e32 v67, v0
	v_mov_b32_e32 v8, v0
	v_mov_b32_e32 v9, v0
	v_mov_b32_e32 v10, v0
	v_mov_b32_e32 v11, v0
	v_mov_b32_e32 v12, v0
	v_mov_b32_e32 v13, v0
	v_mov_b32_e32 v14, v0
	v_mov_b32_e32 v15, v0
	v_mov_b32_e32 v24, v0
	v_mov_b32_e32 v25, v0
	v_mov_b32_e32 v26, v0
	v_mov_b32_e32 v27, v0
	v_mov_b32_e32 v28, v0
	v_mov_b32_e32 v29, v0
	v_mov_b32_e32 v30, v0
	v_mov_b32_e32 v31, v0
	v_mov_b32_e32 v40, v0
	v_mov_b32_e32 v41, v0
	v_mov_b32_e32 v42, v0
	v_mov_b32_e32 v43, v0
	v_mov_b32_e32 v44, v0
	v_mov_b32_e32 v45, v0
	v_mov_b32_e32 v46, v0
	v_mov_b32_e32 v47, v0
	v_mov_b32_e32 v72, v0
	v_mov_b32_e32 v73, v0
	v_mov_b32_e32 v74, v0
	v_mov_b32_e32 v75, v0
	v_mov_b32_e32 v76, v0
	v_mov_b32_e32 v77, v0
	v_mov_b32_e32 v78, v0
	v_mov_b32_e32 v79, v0
	v_mov_b32_e32 v80, v0
	v_mov_b32_e32 v81, v0
	v_mov_b32_e32 v82, v0
	v_mov_b32_e32 v83, v0
	v_mov_b32_e32 v84, v0
	v_mov_b32_e32 v85, v0
	v_mov_b32_e32 v86, v0
	v_mov_b32_e32 v87, v0
	v_mov_b32_e32 v96, v0
	v_mov_b32_e32 v97, v0
	v_mov_b32_e32 v98, v0
	v_mov_b32_e32 v99, v0
	v_mov_b32_e32 v100, v0
	v_mov_b32_e32 v101, v0
	v_mov_b32_e32 v102, v0
	v_mov_b32_e32 v103, v0
	v_mov_b32_e32 v112, v0
	v_mov_b32_e32 v113, v0
	v_mov_b32_e32 v114, v0
	v_mov_b32_e32 v115, v0
	v_mov_b32_e32 v116, v0
	v_mov_b32_e32 v117, v0
	v_mov_b32_e32 v118, v0
	v_mov_b32_e32 v119, v0
	v_mov_b32_e32 v132, v0
	v_mov_b32_e32 v133, v0
	v_mov_b32_e32 v134, v0
	v_mov_b32_e32 v135, v0
	v_mov_b32_e32 v136, v0
	v_mov_b32_e32 v137, v0
	v_mov_b32_e32 v138, v0
	v_mov_b32_e32 v139, v0
	v_mov_b32_e32 v88, v0
	v_mov_b32_e32 v89, v0
	v_mov_b32_e32 v90, v0
	v_mov_b32_e32 v91, v0
	v_mov_b32_e32 v92, v0
	v_mov_b32_e32 v93, v0
	v_mov_b32_e32 v94, v0
	v_mov_b32_e32 v95, v0
	v_mov_b32_e32 v104, v0
	v_mov_b32_e32 v105, v0
	v_mov_b32_e32 v106, v0
	v_mov_b32_e32 v107, v0
	v_mov_b32_e32 v108, v0
	v_mov_b32_e32 v109, v0
	v_mov_b32_e32 v110, v0
	v_mov_b32_e32 v111, v0
	v_mov_b32_e32 v120, v0
	v_mov_b32_e32 v121, v0
	v_mov_b32_e32 v122, v0
	v_mov_b32_e32 v123, v0
	v_mov_b32_e32 v124, v0
	v_mov_b32_e32 v125, v0
	v_mov_b32_e32 v126, v0
	v_mov_b32_e32 v127, v0
	v_mov_b32_e32 v144, v0
	v_mov_b32_e32 v145, v0
	v_mov_b32_e32 v146, v0
	v_mov_b32_e32 v147, v0
	v_mov_b32_e32 v152, v0
	v_mov_b32_e32 v153, v0
	v_mov_b32_e32 v154, v0
	v_mov_b32_e32 v155, v0
	.p2align	6

; template <class Epi, class Sched>
; __device__ __forceinline__ void gemm_phase(PG8_LAS unsigned char* lds, const Gemm g, const Sched& S, const Epi& E) {
;     ...
;         const bool has_next = S.next(ui + 1, nxt);
;         const char* nA = has_next ? (const char*)g.A + (size_t)nxt.pm * tstep : cA; const char* nB = has_next ? (const char*)g.Bt + (size_t)nxt.pn * tstep : cB;
;         for (int t = 0; t < nt; t += 2) {
;             const bool last = (t == nt - 2);
;             const char* a1 = cA + (size_t)(t + 1) * kstep;
;             const char* a2 = last ? nA : cA + (size_t)(t + 2) * kstep; const char* b2 = last ? nB : cB + (size_t)(t + 2) * kstep;
;             const char* a3 = a2 + kstep; const char* b3 = b2 + kstep;
;     ...
; #pragma unroll
;         for (int a = 0; a < 2; ++a)
; #pragma unroll
;             for (int b = 0; b < 2; ++b)
; #pragma unroll
;                 for (int m = 0; m < 4; ++m)
; #pragma unroll
;                     for (int n = 0; n < 2; ++n) acc[a][b][m][n] = (f32x4){0.f, 0.f, 0.f, 0.f};
;         cur = nxt; cA = nA; cB = nB; ++ui;
.LBB0_579:
	v_mov_b64_e32 v[0:1], s[4:5]
	s_ashr_i32 s9, s8, 31
	v_cmp_lt_i64_e32 vcc, s[14:15], v[0:1]
	s_lshl_b64 s[14:15], s[8:9], 20
	s_add_u32 s14, s96, s14
	s_addc_u32 s15, s97, s15
	s_and_b64 s[16:17], vcc, exec
	s_cselect_b32 s9, s15, s19
	s_cselect_b32 s11, s14, s18
	s_ashr_i32 s7, s6, 31
	s_lshl_b64 s[16:17], s[6:7], 20
	v_readlane_b32 s70, v254, 36
	v_readlane_b32 s71, v254, 37
	s_add_u32 s16, s70, s16
	s_addc_u32 s17, s71, s17
	s_and_b64 s[70:71], vcc, exec
	s_cselect_b32 s7, s17, s21
	s_cselect_b32 s81, s16, s20
	s_add_u32 s18, s18, 0x80080
	s_addc_u32 s19, s19, 0
	s_add_u32 s82, s20, 0x100
	v_mov_b32_e32 v0, 0
	s_addc_u32 s83, s21, 0
	s_mov_b32 s88, -2
	v_mov_b32_e32 v1, v0
	v_mov_b32_e32 v2, v0
	v_mov_b32_e32 v3, v0
	v_mov_b32_e32 v4, v0
	v_mov_b32_e32 v5, v0
	v_mov_b32_e32 v6, v0
	v_mov_b32_e32 v7, v0
	v_mov_b32_e32 v8, v0
	v_mov_b32_e32 v9, v0
	v_mov_b32_e32 v10, v0
	v_mov_b32_e32 v11, v0
	v_mov_b32_e32 v16, v0
	v_mov_b32_e32 v17, v0
	v_mov_b32_e32 v18, v0
	v_mov_b32_e32 v19, v0
	v_mov_b32_e32 v24, v0
	v_mov_b32_e32 v25, v0
	v_mov_b32_e32 v26, v0
	v_mov_b32_e32 v27, v0
	v_mov_b32_e32 v32, v0
	v_mov_b32_e32 v33, v0
	v_mov_b32_e32 v34, v0
	v_mov_b32_e32 v35, v0
	v_mov_b32_e32 v40, v0
	v_mov_b32_e32 v41, v0
	v_mov_b32_e32 v42, v0
	v_mov_b32_e32 v43, v0
	v_mov_b32_e32 v48, v0
	v_mov_b32_e32 v49, v0
	v_mov_b32_e32 v50, v0
	v_mov_b32_e32 v51, v0
	v_mov_b32_e32 v12, v0
	v_mov_b32_e32 v13, v0
	v_mov_b32_e32 v14, v0
	v_mov_b32_e32 v15, v0
	v_mov_b32_e32 v20, v0
	v_mov_b32_e32 v21, v0
	v_mov_b32_e32 v22, v0
	v_mov_b32_e32 v23, v0
	v_mov_b32_e32 v28, v0
	v_mov_b32_e32 v29, v0
	v_mov_b32_e32 v30, v0
	v_mov_b32_e32 v31, v0
	v_mov_b32_e32 v36, v0
	v_mov_b32_e32 v37, v0
	v_mov_b32_e32 v38, v0
	v_mov_b32_e32 v39, v0
	v_mov_b32_e32 v44, v0
	v_mov_b32_e32 v45, v0
	v_mov_b32_e32 v46, v0
	v_mov_b32_e32 v47, v0
	v_mov_b32_e32 v52, v0
	v_mov_b32_e32 v53, v0
	v_mov_b32_e32 v54, v0
	v_mov_b32_e32 v55, v0
	v_mov_b32_e32 v56, v0
	v_mov_b32_e32 v57, v0
	v_mov_b32_e32 v58, v0
	v_mov_b32_e32 v59, v0
	v_mov_b32_e32 v60, v0
	v_mov_b32_e32 v61, v0
	v_mov_b32_e32 v62, v0
	v_mov_b32_e32 v63, v0
	v_mov_b32_e32 v64, v0
	v_mov_b32_e32 v65, v0
	v_mov_b32_e32 v66, v0
	v_mov_b32_e32 v67, v0
	v_mov_b32_e32 v68, v0
	v_mov_b32_e32 v69, v0
	v_mov_b32_e32 v70, v0
	v_mov_b32_e32 v71, v0
	v_mov_b32_e32 v72, v0
	v_mov_b32_e32 v73, v0
	v_mov_b32_e32 v74, v0
	v_mov_b32_e32 v75, v0
	v_mov_b32_e32 v80, v0
	v_mov_b32_e32 v81, v0
	v_mov_b32_e32 v82, v0
	v_mov_b32_e32 v83, v0
	v_mov_b32_e32 v88, v0
	v_mov_b32_e32 v89, v0
	v_mov_b32_e32 v90, v0
	v_mov_b32_e32 v91, v0
	v_mov_b32_e32 v96, v0
	v_mov_b32_e32 v97, v0
	v_mov_b32_e32 v98, v0
	v_mov_b32_e32 v99, v0
	v_mov_b32_e32 v104, v0
	v_mov_b32_e32 v105, v0
	v_mov_b32_e32 v106, v0
	v_mov_b32_e32 v107, v0
	v_mov_b32_e32 v112, v0
	v_mov_b32_e32 v113, v0
	v_mov_b32_e32 v114, v0
	v_mov_b32_e32 v115, v0
	v_mov_b32_e32 v76, v0
	v_mov_b32_e32 v77, v0
	v_mov_b32_e32 v78, v0
	v_mov_b32_e32 v79, v0
	v_mov_b32_e32 v84, v0
	v_mov_b32_e32 v85, v0
	v_mov_b32_e32 v86, v0
	v_mov_b32_e32 v87, v0
	v_mov_b32_e32 v92, v0
	v_mov_b32_e32 v93, v0
	v_mov_b32_e32 v94, v0
	v_mov_b32_e32 v95, v0
	v_mov_b32_e32 v100, v0
	v_mov_b32_e32 v101, v0
	v_mov_b32_e32 v102, v0
	v_mov_b32_e32 v103, v0
	v_mov_b32_e32 v108, v0
	v_mov_b32_e32 v109, v0
	v_mov_b32_e32 v110, v0
	v_mov_b32_e32 v111, v0
	v_mov_b32_e32 v116, v0
	v_mov_b32_e32 v117, v0
	v_mov_b32_e32 v118, v0
	v_mov_b32_e32 v119, v0
	v_mov_b32_e32 v120, v0
	v_mov_b32_e32 v121, v0
	v_mov_b32_e32 v122, v0
	v_mov_b32_e32 v123, v0
	v_mov_b32_e32 v124, v0
	v_mov_b32_e32 v125, v0
	v_mov_b32_e32 v126, v0
	v_mov_b32_e32 v127, v0
	.p2align	6

; template <class Epi, class Sched>
; __device__ __forceinline__ void gemm_phase(PG8_LAS unsigned char* lds, const Gemm g, const Sched& S, const Epi& E) {
;     ...
;         const bool has_next = S.next(ui + 1, nxt);
;         const char* nA = has_next ? (const char*)g.A + (size_t)nxt.pm * tstep : cA; const char* nB = has_next ? (const char*)g.Bt + (size_t)nxt.pn * tstep : cB;
;         for (int t = 0; t < nt; t += 2) {
;             const bool last = (t == nt - 2);
;             const char* a1 = cA + (size_t)(t + 1) * kstep;
;             const char* a2 = last ? nA : cA + (size_t)(t + 2) * kstep; const char* b2 = last ? nB : cB + (size_t)(t + 2) * kstep;
;             const char* a3 = a2 + kstep; const char* b3 = b2 + kstep;
;     ...
; #pragma unroll
;         for (int a = 0; a < 2; ++a)
; #pragma unroll
;             for (int b = 0; b < 2; ++b)
; #pragma unroll
;                 for (int m = 0; m < 4; ++m)
; #pragma unroll
;                     for (int n = 0; n < 2; ++n) acc[a][b][m][n] = (f32x4){0.f, 0.f, 0.f, 0.f};
;         cur = nxt; cA = nA; cB = nB; ++ui;
.LBB0_647:
	v_mov_b64_e32 v[0:1], 0x550
	s_ashr_i32 s9, s8, 31
	v_cmp_lt_i64_e32 vcc, s[10:11], v[0:1]
	s_lshl_b64 s[10:11], s[8:9], 19
	s_add_u32 s10, s90, s10
	s_addc_u32 s11, s91, s11
	s_and_b64 s[12:13], vcc, exec
	s_cselect_b32 s9, s11, s15
	s_cselect_b32 s75, s10, s14
	s_ashr_i32 s1, s0, 31
	s_lshl_b64 s[12:13], s[0:1], 19
	s_add_u32 s12, s28, s12
	s_addc_u32 s13, s29, s13
	s_and_b64 s[18:19], vcc, exec
	s_cselect_b32 s1, s13, s17
	s_cselect_b32 s76, s12, s16
	s_add_u32 s14, s14, 0x40080
	s_addc_u32 s15, s15, 0
	s_add_u32 s77, s16, 0x100
	v_mov_b32_e32 v0, 0
	s_addc_u32 s78, s17, 0
	s_mov_b32 s79, -2
	v_mov_b32_e32 v1, v0
	v_mov_b32_e32 v2, v0
	v_mov_b32_e32 v3, v0
	v_mov_b32_e32 v4, v0
	v_mov_b32_e32 v5, v0
	v_mov_b32_e32 v6, v0
	v_mov_b32_e32 v7, v0
	v_mov_b32_e32 v16, v0
	v_mov_b32_e32 v17, v0
	v_mov_b32_e32 v18, v0
	v_mov_b32_e32 v19, v0
	v_mov_b32_e32 v20, v0
	v_mov_b32_e32 v21, v0
	v_mov_b32_e32 v22, v0
	v_mov_b32_e32 v23, v0
	v_mov_b32_e32 v32, v0
	v_mov_b32_e32 v33, v0
	v_mov_b32_e32 v34, v0
	v_mov_b32_e32 v35, v0
	v_mov_b32_e32 v36, v0
	v_mov_b32_e32 v37, v0
	v_mov_b32_e32 v38, v0
	v_mov_b32_e32 v39, v0
	v_mov_b32_e32 v48, v0
	v_mov_b32_e32 v49, v0
	v_mov_b32_e32 v50, v0
	v_mov_b32_e32 v51, v0
	v_mov_b32_e32 v52, v0
	v_mov_b32_e32 v53, v0
	v_mov_b32_e32 v54, v0
	v_mov_b32_e32 v55, v0
	v_mov_b32_e32 v8, v0
	v_mov_b32_e32 v9, v0
	v_mov_b32_e32 v10, v0
	v_mov_b32_e32 v11, v0
	v_mov_b32_e32 v12, v0
	v_mov_b32_e32 v13, v0
	v_mov_b32_e32 v14, v0
	v_mov_b32_e32 v15, v0
	v_mov_b32_e32 v24, v0
	v_mov_b32_e32 v25, v0
	v_mov_b32_e32 v26, v0
	v_mov_b32_e32 v27, v0
	v_mov_b32_e32 v28, v0
	v_mov_b32_e32 v29, v0
	v_mov_b32_e32 v30, v0
	v_mov_b32_e32 v31, v0
	v_mov_b32_e32 v40, v0
	v_mov_b32_e32 v41, v0
	v_mov_b32_e32 v42, v0
	v_mov_b32_e32 v43, v0
	v_mov_b32_e32 v44, v0
	v_mov_b32_e32 v45, v0
	v_mov_b32_e32 v46, v0
	v_mov_b32_e32 v47, v0
	v_mov_b32_e32 v56, v0
	v_mov_b32_e32 v57, v0
	v_mov_b32_e32 v58, v0
	v_mov_b32_e32 v59, v0
	v_mov_b32_e32 v60, v0
	v_mov_b32_e32 v61, v0
	v_mov_b32_e32 v62, v0
	v_mov_b32_e32 v63, v0
	v_mov_b32_e32 v64, v0
	v_mov_b32_e32 v65, v0
	v_mov_b32_e32 v66, v0
	v_mov_b32_e32 v67, v0
	v_mov_b32_e32 v68, v0
	v_mov_b32_e32 v69, v0
	v_mov_b32_e32 v70, v0
	v_mov_b32_e32 v71, v0
	v_mov_b32_e32 v80, v0
	v_mov_b32_e32 v81, v0
	v_mov_b32_e32 v82, v0
	v_mov_b32_e32 v83, v0
	v_mov_b32_e32 v84, v0
	v_mov_b32_e32 v85, v0
	v_mov_b32_e32 v86, v0
	v_mov_b32_e32 v87, v0
	v_mov_b32_e32 v96, v0
	v_mov_b32_e32 v97, v0
	v_mov_b32_e32 v98, v0
	v_mov_b32_e32 v99, v0
	v_mov_b32_e32 v100, v0
	v_mov_b32_e32 v101, v0
	v_mov_b32_e32 v102, v0
	v_mov_b32_e32 v103, v0
	v_mov_b32_e32 v112, v0
	v_mov_b32_e32 v113, v0
	v_mov_b32_e32 v114, v0
	v_mov_b32_e32 v115, v0
	v_mov_b32_e32 v116, v0
	v_mov_b32_e32 v117, v0
	v_mov_b32_e32 v118, v0
	v_mov_b32_e32 v119, v0
	v_mov_b32_e32 v72, v0
	v_mov_b32_e32 v73, v0
	v_mov_b32_e32 v74, v0
	v_mov_b32_e32 v75, v0
	v_mov_b32_e32 v76, v0
	v_mov_b32_e32 v77, v0
	v_mov_b32_e32 v78, v0
	v_mov_b32_e32 v79, v0
	v_mov_b32_e32 v88, v0
	v_mov_b32_e32 v89, v0
	v_mov_b32_e32 v90, v0
	v_mov_b32_e32 v91, v0
	v_mov_b32_e32 v92, v0
	v_mov_b32_e32 v93, v0
	v_mov_b32_e32 v94, v0
	v_mov_b32_e32 v95, v0
	v_mov_b32_e32 v104, v0
	v_mov_b32_e32 v105, v0
	v_mov_b32_e32 v106, v0
	v_mov_b32_e32 v107, v0
	v_mov_b32_e32 v108, v0
	v_mov_b32_e32 v109, v0
	v_mov_b32_e32 v110, v0
	v_mov_b32_e32 v111, v0
	v_mov_b32_e32 v120, v0
	v_mov_b32_e32 v121, v0
	v_mov_b32_e32 v122, v0
	v_mov_b32_e32 v123, v0
	v_mov_b32_e32 v124, v0
	v_mov_b32_e32 v125, v0
	v_mov_b32_e32 v126, v0
	v_mov_b32_e32 v127, v0
	.p2align	6

; #define SBAR() __builtin_amdgcn_sched_barrier(0)
; #define SLOAD(i, k0) do { sr_[i].vs0 = ld8(&Vh[(long)((k0) + sr) * LDK + sc]); sr_[i].vs1 = ld8(&Vh[(long)((k0) + 32 + sr) * LDK + sc]); \
;     sr_[i].ks0 = ld8(&Kh[(long)((k0) + sr) * LDK + sc]); sr_[i].ks1 = ld8(&Kh[(long)((k0) + 32 + sr) * LDK + sc]); } while (0)
; #define SWRITE(b, i) do { *(bf16x8*)((char*)V_lds + (b) * SHM_V + vst0) = sr_[i].vs0;          \
;     *(bf16x8*)((char*)V_lds + (b) * SHM_V + vst1) = sr_[i].vs1; int kc = sc * 2;               \
;     *(bf16x8*)((char*)K_lds + (b) * SHM_K + KSWZ(sr, kc)) = sr_[i].ks0;                       \
;     *(bf16x8*)((char*)K_lds + (b) * SHM_K + KSWZ(32 + sr, kc)) = sr_[i].ks1; } while (0)
; #define SWAIT() asm volatile("s_waitcnt vmcnt(4)" ::: "memory")
; DI void attn_dense_body(const bf16_t* __restrict__ Qb, const bf16_t* __restrict__ Kh, const bf16_t* __restrict__ Vh, ...
;     ...
;   SLOAD(SO, KVBLK); if (2 < NT) SLOAD(SE, 2 * KVBLK);
;   SWAIT(); SWRITE(1, SO); __syncthreads();
;   for (int j = 1; j + 1 < NT; j += 2) {
;     SBAR(); qkt(pB0, pB1, (bf16_t*)((char*)K_lds + SHM_K), qr, r32, hi);
.Lattn_prio_done:
	s_waitcnt lgkmcnt(0)
	s_barrier
	.p2align	6

; template <class Epi, class Sched>
; __device__ __forceinline__ void gemm_phase(PG8_LAS unsigned char* lds, const Gemm g, const Sched& S, const Epi& E) {
;     ...
;         const bool has_next = S.next(ui + 1, nxt);
;         const char* nA = has_next ? (const char*)g.A + (size_t)nxt.pm * tstep : cA; const char* nB = has_next ? (const char*)g.Bt + (size_t)nxt.pn * tstep : cB;
;         for (int t = 0; t < nt; t += 2) {
;             const bool last = (t == nt - 2);
;             const char* a1 = cA + (size_t)(t + 1) * kstep;
;             const char* a2 = last ? nA : cA + (size_t)(t + 2) * kstep; const char* b2 = last ? nB : cB + (size_t)(t + 2) * kstep;
;             const char* a3 = a2 + kstep; const char* b3 = b2 + kstep;
;     ...
; #pragma unroll
;         for (int a = 0; a < 2; ++a)
; #pragma unroll
;             for (int b = 0; b < 2; ++b)
; #pragma unroll
;                 for (int m = 0; m < 4; ++m)
; #pragma unroll
;                     for (int n = 0; n < 2; ++n) acc[a][b][m][n] = (f32x4){0.f, 0.f, 0.f, 0.f};
;         cur = nxt; cA = nA; cB = nB; ++ui;
.LBB0_911:
	v_mov_b64_e32 v[0:1], 0x220
	s_ashr_i32 s7, s6, 31
	v_cmp_lt_i64_e32 vcc, s[8:9], v[0:1]
	s_lshl_b64 s[8:9], s[6:7], 19
	s_add_u32 s8, s58, s8
	s_addc_u32 s9, s59, s9
	s_and_b64 s[10:11], vcc, exec
	s_cselect_b32 s7, s9, s15
	s_cselect_b32 s74, s8, s14
	s_ashr_i32 s5, s4, 31
	s_lshl_b64 s[10:11], s[4:5], 19
	s_add_u32 s10, s54, s10
	s_addc_u32 s11, s55, s11
	s_and_b64 s[18:19], vcc, exec
	s_cselect_b32 s5, s11, s17
	s_cselect_b32 s75, s10, s16
	s_add_u32 s14, s14, 0x40080
	s_addc_u32 s15, s15, 0
	s_add_u32 s76, s16, 0x100
	v_mov_b32_e32 v0, 0
	s_addc_u32 s77, s17, 0
	s_mov_b32 s78, -2
	v_mov_b32_e32 v1, v0
	v_mov_b32_e32 v2, v0
	v_mov_b32_e32 v3, v0
	v_mov_b32_e32 v4, v0
	v_mov_b32_e32 v5, v0
	v_mov_b32_e32 v6, v0
	v_mov_b32_e32 v7, v0
	v_mov_b32_e32 v8, v0
	v_mov_b32_e32 v9, v0
	v_mov_b32_e32 v10, v0
	v_mov_b32_e32 v11, v0
	v_mov_b32_e32 v16, v0
	v_mov_b32_e32 v17, v0
	v_mov_b32_e32 v18, v0
	v_mov_b32_e32 v19, v0
	v_mov_b32_e32 v24, v0
	v_mov_b32_e32 v25, v0
	v_mov_b32_e32 v26, v0
	v_mov_b32_e32 v27, v0
	v_mov_b32_e32 v32, v0
	v_mov_b32_e32 v33, v0
	v_mov_b32_e32 v34, v0
	v_mov_b32_e32 v35, v0
	v_mov_b32_e32 v40, v0
	v_mov_b32_e32 v41, v0
	v_mov_b32_e32 v42, v0
	v_mov_b32_e32 v43, v0
	v_mov_b32_e32 v48, v0
	v_mov_b32_e32 v49, v0
	v_mov_b32_e32 v50, v0
	v_mov_b32_e32 v51, v0
	v_mov_b32_e32 v12, v0
	v_mov_b32_e32 v13, v0
	v_mov_b32_e32 v14, v0
	v_mov_b32_e32 v15, v0
	v_mov_b32_e32 v20, v0
	v_mov_b32_e32 v21, v0
	v_mov_b32_e32 v22, v0
	v_mov_b32_e32 v23, v0
	v_mov_b32_e32 v28, v0
	v_mov_b32_e32 v29, v0
	v_mov_b32_e32 v30, v0
	v_mov_b32_e32 v31, v0
	v_mov_b32_e32 v36, v0
	v_mov_b32_e32 v37, v0
	v_mov_b32_e32 v38, v0
	v_mov_b32_e32 v39, v0
	v_mov_b32_e32 v44, v0
	v_mov_b32_e32 v45, v0
	v_mov_b32_e32 v46, v0
	v_mov_b32_e32 v47, v0
	v_mov_b32_e32 v52, v0
	v_mov_b32_e32 v53, v0
	v_mov_b32_e32 v54, v0
	v_mov_b32_e32 v55, v0
	v_mov_b32_e32 v56, v0
	v_mov_b32_e32 v57, v0
	v_mov_b32_e32 v58, v0
	v_mov_b32_e32 v59, v0
	v_mov_b32_e32 v60, v0
	v_mov_b32_e32 v61, v0
	v_mov_b32_e32 v62, v0
	v_mov_b32_e32 v63, v0
	v_mov_b32_e32 v64, v0
	v_mov_b32_e32 v65, v0
	v_mov_b32_e32 v66, v0
	v_mov_b32_e32 v67, v0
	v_mov_b32_e32 v68, v0
	v_mov_b32_e32 v69, v0
	v_mov_b32_e32 v70, v0
	v_mov_b32_e32 v71, v0
	v_mov_b32_e32 v72, v0
	v_mov_b32_e32 v73, v0
	v_mov_b32_e32 v74, v0
	v_mov_b32_e32 v75, v0
	v_mov_b32_e32 v80, v0
	v_mov_b32_e32 v81, v0
	v_mov_b32_e32 v82, v0
	v_mov_b32_e32 v83, v0
	v_mov_b32_e32 v88, v0
	v_mov_b32_e32 v89, v0
	v_mov_b32_e32 v90, v0
	v_mov_b32_e32 v91, v0
	v_mov_b32_e32 v96, v0
	v_mov_b32_e32 v97, v0
	v_mov_b32_e32 v98, v0
	v_mov_b32_e32 v99, v0
	v_mov_b32_e32 v104, v0
	v_mov_b32_e32 v105, v0
	v_mov_b32_e32 v106, v0
	v_mov_b32_e32 v107, v0
	v_mov_b32_e32 v112, v0
	v_mov_b32_e32 v113, v0
	v_mov_b32_e32 v114, v0
	v_mov_b32_e32 v115, v0
	v_mov_b32_e32 v76, v0
	v_mov_b32_e32 v77, v0
	v_mov_b32_e32 v78, v0
	v_mov_b32_e32 v79, v0
	v_mov_b32_e32 v84, v0
	v_mov_b32_e32 v85, v0
	v_mov_b32_e32 v86, v0
	v_mov_b32_e32 v87, v0
	v_mov_b32_e32 v92, v0
	v_mov_b32_e32 v93, v0
	v_mov_b32_e32 v94, v0
	v_mov_b32_e32 v95, v0
	v_mov_b32_e32 v100, v0
	v_mov_b32_e32 v101, v0
	v_mov_b32_e32 v102, v0
	v_mov_b32_e32 v103, v0
	v_mov_b32_e32 v108, v0
	v_mov_b32_e32 v109, v0
	v_mov_b32_e32 v110, v0
	v_mov_b32_e32 v111, v0
	v_mov_b32_e32 v116, v0
	v_mov_b32_e32 v117, v0
	v_mov_b32_e32 v118, v0
	v_mov_b32_e32 v119, v0
	v_mov_b32_e32 v120, v0
	v_mov_b32_e32 v121, v0
	v_mov_b32_e32 v122, v0
	v_mov_b32_e32 v123, v0
	v_mov_b32_e32 v124, v0
	v_mov_b32_e32 v125, v0
	v_mov_b32_e32 v126, v0
	v_mov_b32_e32 v127, v0
	.p2align	6

; DI void ln_phase(const Args& a, int l) {
;     ...
; #pragma unroll 1
;         for (int r0 = 0; r0 < 15; r0 += 3) ln_rows<3>(a, l, gw * 16 + r0, lane, lgv, lbv, gate, sh, sc1);
;         ln_rows<1>(a, l, gw * 16 + 15, lane, lgv, lbv, gate, sh, sc1);
.LBB0_974:
	s_add_i32 s69, s69, 3
	s_mov_b64 s[6:7], 0x1800
	v_lshl_add_u64 v[124:125], v[124:125], 0, s[6:7]
	v_lshl_add_u64 v[126:127], v[126:127], 0, s[92:93]
	s_cmp_gt_u32 s69, 11
	v_lshl_add_u64 v[128:129], v[128:129], 0, s[92:93]
	s_cbranch_scc1 .LBB0_999
	.p2align	6
